# weight copies other than Wqkv0 deferred from the prologue to the workgroups idle in the last (48-tile) layer-0 QKV GEMM round; long branches via trampolines
# speedup vs baseline: 1.0050x; 1.0050x over previous
; #define LAS __attribute__((address_space(3)))
; __device__ __forceinline__ void transpose_item(const float* W, int K, int N, bf16_t* WT, bool perm, LAS float* scr, int item, int lane) {
;     const int nblk = N / 32, kb = item / nblk, nb = item % nblk, k0 = 64 * kb, n0 = 32 * nb;
;     const int r0 = perm ? ((n0 & ~255) + 128 * ((n0 >> 5) & 1) + 32 * ((n0 >> 6) & 3)) : n0;
; #pragma unroll
;     for (int i = 0; i < 32; ++i) { const int kk = 2 * i + (lane >> 5); scr[kk * 33 + (lane & 31)] = W[(size_t)(k0 + kk) * N + n0 + (lane & 31)]; }
;     asm volatile("s_waitcnt lgkmcnt(0)" ::: "memory");
;     const int c = lane & 7;
; #pragma unroll
;     for (int j = 0; j < 4; ++j) { const int n = (lane >> 3) + 8 * j; const LAS float* s = scr + (8 * c) * 33 + n;
;         u32x4 o; o.x = pkbf(s[0 * 33], s[1 * 33]); o.y = pkbf(s[2 * 33], s[3 * 33]); o.z = pkbf(s[4 * 33], s[5 * 33]); o.w = pkbf(s[6 * 33], s[7 * 33]);
;         *(u32x4*)(WT + (size_t)(r0 + n) * K + k0 + 8 * c) = o; }
;     asm volatile("s_waitcnt lgkmcnt(0)" ::: "memory");
; }
; __device__ __forceinline__ void prologue_phase(const Args& a, LAS unsigned char* lds) {
;     ...
;     for (int k = 0;; ++k) {
;         int it;
;         if (pre && k < HCAP) { if ((int)blockIdx.x < 96) continue; it = fw + k * nfree; }
;         else { it = pre + gw + (k - (pre ? HCAP : 0)) * ngw; if (it >= NITEMS) break; }
;         int r = it;
;         if (r < I_QKV0) { transpose_item(a.na_wqkv, DM, 3072, (bf16_t*)(a.ws + WS_WQKV0), true, scr, r, lane); continue; } r -= I_QKV0;
;         if (r < I_WO) { transpose_item(a.na_wo, DM, DM, (bf16_t*)(a.ws + WS_WO0), false, scr, r, lane); continue; } r -= I_WO;
;         if (r < I_QKV1) { transpose_item(a.swa_wqkv, DM, 1536, (bf16_t*)(a.ws + WS_WQKV1), true, scr, r, lane); continue; } r -= I_QKV1;
;         if (r < I_WO) { transpose_item(a.swa_wo, DM, DM, (bf16_t*)(a.ws + WS_WO1), false, scr, r, lane); continue; } r -= I_WO;
;         if (r < 2 * I_W1) { const int l = r / I_W1; transpose_item(a.mlp_w1 + (size_t)l * DM * DFF, DM, DFF, (bf16_t*)(a.ws + WS_W1) + (size_t)l * DM * DFF, false, scr, r % I_W1, lane); continue; } r -= 2 * I_W1;
;         { const int l = r / I_W2; transpose_item(a.mlp_w2 + (size_t)l * DM * DFF, DFF, DM, (bf16_t*)(a.ws + WS_W2) + (size_t)l * DM * DFF, false, scr, r % I_W2, lane); }
.LBB0_53:
	s_andn2_b64 vcc, exec, s[0:1]
	s_cbranch_vccnz .LBB0_74
	s_cmpk_gt_i32 s27, 0x5ff
	s_mov_b64 s[0:1], -1
	s_cbranch_scc0 .LBB0_72
	s_cmp_eq_u32 s56, 0x800
	s_cbranch_scc0 .Lpro_full
	s_mov_b32 s8, 40
	s_branch .LBB0_74
.Lpro_full:
	s_cmpk_gt_u32 s27, 0x7ff
	s_cbranch_scc0 .LBB0_69
	s_cmpk_gt_u32 s27, 0xaff
	s_cbranch_scc0 .LBB0_66
	s_cmpk_gt_u32 s27, 0xcff
	s_cbranch_scc0 .LBB0_63
	s_cmpk_gt_u32 s27, 0x1cff
	v_lshlrev_b32_e32 v2, 2, v0
	v_lshlrev_b32_e32 v22, 1, v4
	s_cbranch_scc0 .LBB0_60
	s_add_i32 s28, s27, 0xffffe300
	s_lshr_b32 s0, s28, 1
	s_and_b32 s8, s0, 0x7ffffc00
	s_lshl_b64 s[0:1], s[8:9], 14
	s_add_u32 s29, s6, s0
	s_addc_u32 s30, s7, s1
	s_lshl_b64 s[14:15], s[8:9], 13
	s_add_u32 s1, s19, s14
	s_addc_u32 s8, s20, s15
	s_lshl_b32 s0, s28, 1
	s_and_b32 s14, s0, 0xfc0
	v_or_b32_e32 v23, s14, v1
	v_lshlrev_b32_e32 v68, 12, v23
	v_or_b32_e32 v23, s14, v27
	s_lshl_b32 s0, s27, 5
	v_lshlrev_b32_e32 v70, 12, v23
	v_or_b32_e32 v23, s14, v28
	s_and_b32 s0, s0, 0x3e0
	v_lshlrev_b32_e32 v72, 12, v23
	v_or_b32_e32 v23, s14, v29
	s_lshl_b32 s15, s0, 2
	v_lshlrev_b32_e32 v74, 12, v23
	v_or_b32_e32 v23, s14, v30
	s_add_u32 s28, s29, s15
	v_lshlrev_b32_e32 v76, 12, v23
	v_or_b32_e32 v23, s14, v31
	s_addc_u32 s29, s30, 0
	v_lshlrev_b32_e32 v78, 12, v23
	v_or_b32_e32 v23, s14, v32
	v_lshl_add_u64 v[24:25], s[28:29], 0, v[2:3]
	v_mov_b32_e32 v69, v3
	v_lshlrev_b32_e32 v80, 12, v23
	v_or_b32_e32 v23, s14, v34
	v_lshl_add_u64 v[68:69], v[24:25], 0, v[68:69]
	v_mov_b32_e32 v71, v3
	v_mov_b32_e32 v73, v3
	v_mov_b32_e32 v75, v3
	v_mov_b32_e32 v77, v3
	v_mov_b32_e32 v79, v3
	v_mov_b32_e32 v81, v3
	v_lshlrev_b32_e32 v82, 12, v23
	v_mov_b32_e32 v83, v3
	v_lshl_add_u64 v[70:71], v[24:25], 0, v[70:71]
	v_lshl_add_u64 v[72:73], v[24:25], 0, v[72:73]
	v_lshl_add_u64 v[74:75], v[24:25], 0, v[74:75]
	v_lshl_add_u64 v[76:77], v[24:25], 0, v[76:77]
	v_lshl_add_u64 v[78:79], v[24:25], 0, v[78:79]
	v_lshl_add_u64 v[80:81], v[24:25], 0, v[80:81]
	v_lshl_add_u64 v[82:83], v[24:25], 0, v[82:83]
	global_load_dword v23, v[68:69], off
	global_load_dword v67, v[70:71], off
	global_load_dword v84, v[72:73], off
	global_load_dword v85, v[74:75], off
	global_load_dword v86, v[76:77], off
	global_load_dword v87, v[78:79], off
	global_load_dword v88, v[80:81], off
	global_load_dword v89, v[82:83], off
	v_or_b32_e32 v68, s14, v35
	v_lshlrev_b32_e32 v68, 12, v68
	v_mov_b32_e32 v69, v3
	v_or_b32_e32 v70, s14, v36
	v_or_b32_e32 v72, s14, v37
	v_or_b32_e32 v74, s14, v38
	v_or_b32_e32 v76, s14, v39
	v_or_b32_e32 v78, s14, v41
	v_or_b32_e32 v80, s14, v42
	v_or_b32_e32 v82, s14, v43
	v_lshl_add_u64 v[68:69], v[24:25], 0, v[68:69]
	v_lshlrev_b32_e32 v70, 12, v70
	v_mov_b32_e32 v71, v3
	v_lshlrev_b32_e32 v72, 12, v72
	v_mov_b32_e32 v73, v3
	v_lshlrev_b32_e32 v74, 12, v74
	v_mov_b32_e32 v75, v3
	v_lshlrev_b32_e32 v76, 12, v76
	v_mov_b32_e32 v77, v3
	v_lshlrev_b32_e32 v78, 12, v78
	v_mov_b32_e32 v79, v3
	v_lshlrev_b32_e32 v80, 12, v80
	v_mov_b32_e32 v81, v3
	v_lshlrev_b32_e32 v82, 12, v82
	v_mov_b32_e32 v83, v3
	v_lshl_add_u64 v[70:71], v[24:25], 0, v[70:71]
	v_lshl_add_u64 v[72:73], v[24:25], 0, v[72:73]
	v_lshl_add_u64 v[74:75], v[24:25], 0, v[74:75]
	v_lshl_add_u64 v[76:77], v[24:25], 0, v[76:77]
	v_lshl_add_u64 v[78:79], v[24:25], 0, v[78:79]
	v_lshl_add_u64 v[80:81], v[24:25], 0, v[80:81]
	v_lshl_add_u64 v[82:83], v[24:25], 0, v[82:83]
	global_load_dword v90, v[68:69], off
	global_load_dword v91, v[70:71], off
	global_load_dword v92, v[72:73], off
	global_load_dword v93, v[74:75], off
	global_load_dword v94, v[76:77], off
	global_load_dword v95, v[78:79], off
	global_load_dword v96, v[80:81], off
	global_load_dword v97, v[82:83], off
	v_or_b32_e32 v68, s14, v44
	v_lshlrev_b32_e32 v68, 12, v68
	v_mov_b32_e32 v69, v3
	v_or_b32_e32 v70, s14, v45
	v_or_b32_e32 v72, s14, v46
	v_or_b32_e32 v74, s14, v48
	v_or_b32_e32 v76, s14, v49
	v_or_b32_e32 v78, s14, v50
	v_or_b32_e32 v80, s14, v51
	v_or_b32_e32 v82, s14, v52
	v_lshl_add_u64 v[68:69], v[24:25], 0, v[68:69]
	v_lshlrev_b32_e32 v70, 12, v70
	v_mov_b32_e32 v71, v3
	v_lshlrev_b32_e32 v72, 12, v72
	v_mov_b32_e32 v73, v3
	v_lshlrev_b32_e32 v74, 12, v74
	v_mov_b32_e32 v75, v3
	v_lshlrev_b32_e32 v76, 12, v76
	v_mov_b32_e32 v77, v3
	v_lshlrev_b32_e32 v78, 12, v78
	v_mov_b32_e32 v79, v3
	v_lshlrev_b32_e32 v80, 12, v80
	v_mov_b32_e32 v81, v3
	v_lshlrev_b32_e32 v82, 12, v82
	v_mov_b32_e32 v83, v3
	v_lshl_add_u64 v[70:71], v[24:25], 0, v[70:71]
	v_lshl_add_u64 v[72:73], v[24:25], 0, v[72:73]
	v_lshl_add_u64 v[74:75], v[24:25], 0, v[74:75]
	v_lshl_add_u64 v[76:77], v[24:25], 0, v[76:77]
	v_lshl_add_u64 v[78:79], v[24:25], 0, v[78:79]
	v_lshl_add_u64 v[80:81], v[24:25], 0, v[80:81]
	v_lshl_add_u64 v[82:83], v[24:25], 0, v[82:83]
	global_load_dword v98, v[68:69], off
	global_load_dword v99, v[70:71], off
	global_load_dword v100, v[72:73], off
	global_load_dword v101, v[74:75], off
	global_load_dword v102, v[76:77], off
	global_load_dword v103, v[78:79], off
	global_load_dword v104, v[80:81], off
	global_load_dword v105, v[82:83], off
	v_or_b32_e32 v68, s14, v53
	v_lshlrev_b32_e32 v68, 12, v68
	v_mov_b32_e32 v69, v3
	v_or_b32_e32 v70, s14, v55
	v_or_b32_e32 v72, s14, v56
	v_or_b32_e32 v74, s14, v57
	v_or_b32_e32 v76, s14, v58
	v_or_b32_e32 v78, s14, v59
	v_or_b32_e32 v80, s14, v60
	v_or_b32_e32 v82, s14, v61
	v_lshl_add_u64 v[68:69], v[24:25], 0, v[68:69]
	v_lshlrev_b32_e32 v70, 12, v70
	v_mov_b32_e32 v71, v3
	v_lshlrev_b32_e32 v72, 12, v72
	v_mov_b32_e32 v73, v3
	v_lshlrev_b32_e32 v74, 12, v74
	v_mov_b32_e32 v75, v3
	v_lshlrev_b32_e32 v76, 12, v76
	v_mov_b32_e32 v77, v3
	v_lshlrev_b32_e32 v78, 12, v78
	v_mov_b32_e32 v79, v3
	v_lshlrev_b32_e32 v80, 12, v80
	v_mov_b32_e32 v81, v3
	v_lshlrev_b32_e32 v82, 12, v82
	v_mov_b32_e32 v83, v3
	v_lshl_add_u64 v[70:71], v[24:25], 0, v[70:71]
	v_lshl_add_u64 v[72:73], v[24:25], 0, v[72:73]
	v_lshl_add_u64 v[74:75], v[24:25], 0, v[74:75]
	v_lshl_add_u64 v[76:77], v[24:25], 0, v[76:77]
	v_lshl_add_u64 v[78:79], v[24:25], 0, v[78:79]
	v_lshl_add_u64 v[80:81], v[24:25], 0, v[80:81]
	v_lshl_add_u64 v[24:25], v[24:25], 0, v[82:83]
	global_load_dword v82, v[68:69], off
	global_load_dword v83, v[70:71], off
	global_load_dword v106, v[72:73], off
	global_load_dword v107, v[74:75], off
	global_load_dword v108, v[76:77], off
	global_load_dword v109, v[78:79], off
	global_load_dword v110, v[80:81], off
	global_load_dword v111, v[24:25], off
	v_add_u32_e32 v24, v5, v26
	s_waitcnt vmcnt(30)
; #define LAS __attribute__((address_space(3)))
; __device__ __forceinline__ unsigned pkbf(float lo, float hi) { f32x2_t v = {lo, hi}; bf16x2_t b = __builtin_convertvector(v, bf16x2_t); return __builtin_bit_cast(unsigned, b); }
; __device__ __forceinline__ void transpose_item(const float* W, int K, int N, bf16_t* WT, bool perm, LAS float* scr, int item, int lane) {
;     ...
;     for (int i = 0; i < 32; ++i) { const int kk = 2 * i + (lane >> 5); scr[kk * 33 + (lane & 31)] = W[(size_t)(k0 + kk) * N + n0 + (lane & 31)]; }
;     asm volatile("s_waitcnt lgkmcnt(0)" ::: "memory");
;     const int c = lane & 7;
; #pragma unroll
;     for (int j = 0; j < 4; ++j) { const int n = (lane >> 3) + 8 * j; const LAS float* s = scr + (8 * c) * 33 + n;
;         u32x4 o; o.x = pkbf(s[0 * 33], s[1 * 33]); o.y = pkbf(s[2 * 33], s[3 * 33]); o.z = pkbf(s[4 * 33], s[5 * 33]); o.w = pkbf(s[6 * 33], s[7 * 33]);
;         *(u32x4*)(WT + (size_t)(r0 + n) * K + k0 + 8 * c) = o; }
;     asm volatile("s_waitcnt lgkmcnt(0)" ::: "memory");
	ds_write2_b32 v24, v23, v67 offset1:66
	s_waitcnt vmcnt(28)
	ds_write2_b32 v24, v84, v85 offset0:132 offset1:198
	v_add_u32_e32 v23, 0x400, v24
	s_waitcnt vmcnt(26)
	ds_write2_b32 v23, v86, v87 offset0:8 offset1:74
	v_add_u32_e32 v23, v5, v33
	s_waitcnt vmcnt(24)
	ds_write2_b32 v23, v88, v89 offset1:66
	s_waitcnt vmcnt(22)
	ds_write2_b32 v23, v90, v91 offset0:132 offset1:198
	v_add_u32_e32 v23, 0x400, v23
	s_waitcnt vmcnt(20)
	ds_write2_b32 v23, v92, v93 offset0:8 offset1:74
	v_add_u32_e32 v23, v5, v40
	s_waitcnt vmcnt(18)
	ds_write2_b32 v23, v94, v95 offset1:66
	s_waitcnt vmcnt(16)
	ds_write2_b32 v23, v96, v97 offset0:132 offset1:198
	v_add_u32_e32 v23, 0x400, v23
	s_lshl_b32 s14, s14, 1
	s_add_u32 s14, s1, s14
	s_addc_u32 s15, s8, 0
	v_mov_b32_e32 v89, v3
	s_waitcnt vmcnt(14)
	ds_write2_b32 v23, v98, v99 offset0:8 offset1:74
	v_add_u32_e32 v23, v5, v47
	s_waitcnt vmcnt(12)
	ds_write2_b32 v23, v100, v101 offset1:66
	s_waitcnt vmcnt(10)
	ds_write2_b32 v23, v102, v103 offset0:132 offset1:198
	v_add_u32_e32 v23, 0x400, v23
	s_waitcnt vmcnt(8)
	ds_write2_b32 v23, v104, v105 offset0:8 offset1:74
	v_add_u32_e32 v23, v5, v54
	s_waitcnt vmcnt(6)
	ds_write2_b32 v23, v82, v83 offset1:66
	s_waitcnt vmcnt(4)
	ds_write2_b32 v23, v106, v107 offset0:132 offset1:198
	v_add_u32_e32 v23, 0x400, v23
	s_waitcnt vmcnt(2)
	ds_write2_b32 v23, v108, v109 offset0:8 offset1:74
	s_waitcnt vmcnt(0)
	ds_write2_b32 v23, v110, v111 offset0:140 offset1:206
	s_waitcnt lgkmcnt(0)
	ds_read2_b32 v[24:25], v63 offset0:33 offset1:41
	ds_read2_b32 v[72:73], v63 offset1:8
	ds_read2_b32 v[74:75], v63 offset0:66 offset1:74
	ds_read2_b32 v[76:77], v63 offset0:99 offset1:107
	ds_read2_b32 v[78:79], v63 offset0:132 offset1:140
	ds_read2_b32 v[80:81], v63 offset0:165 offset1:173
	ds_read2_b32 v[82:83], v63 offset0:198 offset1:206
	ds_read2_b32 v[84:85], v63 offset0:231 offset1:239
	v_mov_b32_e32 v23, v3
	v_lshl_add_u64 v[86:87], s[14:15], 0, v[22:23]
	v_or_b32_e32 v23, s0, v62
	v_lshlrev_b32_e32 v88, 13, v23
	s_waitcnt lgkmcnt(6)
	v_cvt_pk_bf16_f32 v68, v72, v24
	s_waitcnt lgkmcnt(4)
	v_cvt_pk_bf16_f32 v69, v74, v76
	s_waitcnt lgkmcnt(2)
	v_cvt_pk_bf16_f32 v70, v78, v80
	s_waitcnt lgkmcnt(0)
	v_cvt_pk_bf16_f32 v71, v82, v84
	v_lshl_add_u64 v[88:89], v[86:87], 0, v[88:89]
	global_store_dwordx4 v[88:89], v[68:71], off
	v_or_b32_e32 v23, s0, v64
	v_lshlrev_b32_e32 v24, 13, v23
	v_cvt_pk_bf16_f32 v68, v73, v25
	v_cvt_pk_bf16_f32 v69, v75, v77
	v_cvt_pk_bf16_f32 v70, v79, v81
	v_cvt_pk_bf16_f32 v71, v83, v85
	ds_read2_b32 v[72:73], v63 offset0:49 offset1:57
	ds_read2_b32 v[74:75], v63 offset0:16 offset1:24
	ds_read2_b32 v[76:77], v63 offset0:82 offset1:90
	ds_read2_b32 v[78:79], v63 offset0:115 offset1:123
	ds_read2_b32 v[80:81], v63 offset0:148 offset1:156
	ds_read2_b32 v[82:83], v63 offset0:181 offset1:189
	ds_read2_b32 v[84:85], v63 offset0:214 offset1:222
	ds_read2_b32 v[88:89], v63 offset0:247 offset1:255
	v_mov_b32_e32 v25, v3
	v_lshl_add_u64 v[24:25], v[86:87], 0, v[24:25]
	v_or_b32_e32 v23, s0, v65
	global_store_dwordx4 v[24:25], v[68:71], off
	v_lshlrev_b32_e32 v24, 13, v23
	v_mov_b32_e32 v25, v3
	s_waitcnt lgkmcnt(6)
	v_cvt_pk_bf16_f32 v68, v74, v72
	s_waitcnt lgkmcnt(4)
	v_cvt_pk_bf16_f32 v69, v76, v78
	s_waitcnt lgkmcnt(2)
	v_cvt_pk_bf16_f32 v70, v80, v82
	s_waitcnt lgkmcnt(0)
	v_cvt_pk_bf16_f32 v71, v84, v88
	v_lshl_add_u64 v[24:25], v[86:87], 0, v[24:25]
	v_or_b32_e32 v23, s0, v66
	global_store_dwordx4 v[24:25], v[68:71], off
	v_lshlrev_b32_e32 v24, 13, v23
	v_mov_b32_e32 v25, v3
	v_cvt_pk_bf16_f32 v68, v75, v73
	v_cvt_pk_bf16_f32 v69, v77, v79
	v_cvt_pk_bf16_f32 v70, v81, v83
	v_cvt_pk_bf16_f32 v71, v85, v89
	v_lshl_add_u64 v[24:25], v[86:87], 0, v[24:25]
	global_store_dwordx4 v[24:25], v[68:71], off
	s_waitcnt lgkmcnt(0)
	s_mov_b64 s[0:1], 0

; __global__ void __launch_bounds__(512, 2) fwd_megakernel(Args a) {
;     ...
;     for (int l = 0; l < 2; ++l) {
;         const int M = l == 0 ? MALL : MLAT;
;     ...
; #pragma unroll 1
;         for (int rep = 0; rep < NORM_REP; ++rep) {
;         norm_phase(l == 0 ? (const void*)A->x : (const void*)WSP(bf16_t, WS_HB), l == 0, l == 0 ? A->ctx : WSP(float, WS_HC), MALL, A->g_mix + l * DM, WSP(float, WS_MODS) + l * 5 * 6144, 0, 1024, WSP(bf16_t, WS_U), WSP(const float, WS_PART), l == 0 ? 0 : 16, WSP(float, WS_HC));
;     ...
;         }
;         {
;             const int N = l == 0 ? 3072 : 1536;
;             pg8::Gemm g{WSP(bf16_t, WS_U), WSP(const bf16_t, l == 0 ? WS_WQKV0 : WS_WQKV1), MALL, N, DM, 2}; pg8::StaticOrder S; S.init(MALL, N, gridDim.x, blockIdx.x);
;             EpiQKV E{WSP(bf16_t, WS_Q), (size_t)(WS_K - WS_Q) / 2, l == 0 ? DM : 256, l == 0 ? 4 : 1, WSP(float, WS_GAINS) + l * 128, l == 0 ? nullptr : WSP(const float, WS_ROPE)};
;             pg8::gemm_phase<EpiQKV, pg8::StaticOrder, true, true>(lds, g, S, E);
;         }
;     ...
; #pragma unroll 1
;         for (int rep = 0; rep < ATT_REP; ++rep) {
;         if (l == 0) att::na_phase(lds, WSP(bf16_t, WS_Q), WSP(bf16_t, WS_K), WSP(bf16_t, WS_V), WSP(bf16_t, WS_O), A->na_rpb, -WSP(const float, WS_BND)[0]);
;         else att::swa_phase(lds, WSP(bf16_t, WS_Q), WSP(bf16_t, WS_K), WSP(bf16_t, WS_V), WSP(bf16_t, WS_O), A->swa_sink, -WSP(const float, WS_BND)[1]);
;     ...
;         }
;         {
;             pg8::Gemm g{WSP(bf16_t, WS_O), WSP(const bf16_t, l == 0 ? WS_WO0 : WS_WO1), M, DM, DM, 2}; SplitOrder S; S.init(DM, DM, l == 0 ? 4 : 0, gridDim.x, blockIdx.x);
;             EpiRes E{l == 0 ? (const void*)A->x : (const void*)WSP(bf16_t, WS_HB), WSP(float, WS_HC), WSP(bf16_t, WS_HB), WSP(float, WS_HC), WSP(float, WS_MODS) + l * 5 * 6144 + 2048, WSP(float, WS_PART), l == 0, 0};
;             pg8::gemm_phase<EpiRes, SplitOrder, true, true>(lds, g, S, E);
;         }
;     ...
; #pragma unroll 1
;         for (int rep = 0; rep < NORM_REP; ++rep) {
;         norm_phase(WSP(bf16_t, WS_HB), 0, l == 0 ? A->ctx : WSP(float, WS_HC), M, A->g_mlp + l * DM, WSP(float, WS_MODS) + l * 5 * 6144, 3072, 4096, WSP(bf16_t, WS_U), WSP(const float, WS_PART), l == 0 ? 4 : 0, WSP(float, WS_HC));
;     ...
;         }
;     ...
; #pragma unroll 1
;         for (int rep = 0; rep < UP_REP; ++rep) {
;     ...
;         {
.Ltramp_fwd:
	s_branch .LBB0_1103

; #define PG8_WAIT_V(n) asm volatile("s_waitcnt vmcnt(" #n ")" ::: "memory")
; #define PG8_BAR __builtin_amdgcn_s_barrier()
; #define LAS __attribute__((address_space(3)))
; __device__ __forceinline__ unsigned pkbf(float lo, float hi) { f32x2_t v = {lo, hi}; bf16x2_t b = __builtin_convertvector(v, bf16x2_t); return __builtin_bit_cast(unsigned, b); }
; template <class Epi, class Sched, bool ALIGN_EPI = false, bool SP2 = false>
; __device__ __forceinline__ void gemm_phase(PG8_LAS unsigned char* lds, const Gemm g, const Sched& S, const Epi& E) {
;     ...
;     PG8_WAIT_V(0);
;     if constexpr (!ALIGN_EPI) { if (wr == 0) PG8_BAR; }
;     PG8_BAR;
; __device__ __forceinline__ void transpose_item(const float* W, int K, int N, bf16_t* WT, bool perm, LAS float* scr, int item, int lane) {
;     const int nblk = N / 32, kb = item / nblk, nb = item % nblk, k0 = 64 * kb, n0 = 32 * nb;
;     const int r0 = perm ? ((n0 & ~255) + 128 * ((n0 >> 5) & 1) + 32 * ((n0 >> 6) & 3)) : n0;
; #pragma unroll
;     for (int i = 0; i < 32; ++i) { const int kk = 2 * i + (lane >> 5); scr[kk * 33 + (lane & 31)] = W[(size_t)(k0 + kk) * N + n0 + (lane & 31)]; }
;     asm volatile("s_waitcnt lgkmcnt(0)" ::: "memory");
;     const int c = lane & 7;
; #pragma unroll
;     for (int j = 0; j < 4; ++j) { const int n = (lane >> 3) + 8 * j; const LAS float* s = scr + (8 * c) * 33 + n;
;         u32x4 o; o.x = pkbf(s[0 * 33], s[1 * 33]); o.y = pkbf(s[2 * 33], s[3 * 33]); o.z = pkbf(s[4 * 33], s[5 * 33]); o.w = pkbf(s[6 * 33], s[7 * 33]);
;         *(u32x4*)(WT + (size_t)(r0 + n) * K + k0 + 8 * c) = o; }
;     asm volatile("s_waitcnt lgkmcnt(0)" ::: "memory");
; }
.LBB0_287:
	s_waitcnt vmcnt(0)
	v_readlane_b32 s54, v240, 23
	v_readlane_b32 s52, v240, 27
	v_readlane_b32 s50, v240, 29
	v_readlane_b32 s55, v240, 24
	v_readlane_b32 s56, v240, 25
	v_readlane_b32 s53, v240, 28
	v_readlane_b32 s51, v240, 30
	s_barrier
	v_readlane_b32 s57, v240, 26
	v_readlane_b32 s6, v240, 36
	v_readlane_b32 s8, v241, 2
	v_readlane_b32 s9, v241, 3
	s_cmp_eq_u32 s6, 0
	s_cbranch_scc1 .Ldw_done
	s_load_dword s7, s[8:9], 0x0
	s_waitcnt lgkmcnt(0)
	s_cmp_lg_u32 s7, 0x100
	s_cbranch_scc1 .Ldw_done
	s_cmp_lt_u32 s2, 48
	s_cbranch_scc1 .Ldw_done
	global_load_dwordx2 v[40:41], v155, s[78:79] offset:112
	global_load_dwordx2 v[42:43], v155, s[78:79] offset:120
	global_load_dwordx2 v[44:45], v155, s[78:79] offset:152
	global_load_dwordx2 v[46:47], v155, s[78:79] offset:64
	global_load_dwordx2 v[48:49], v155, s[78:79] offset:72
	v_and_b32_e32 v32, 63, v152
	v_and_b32_e32 v33, 31, v32
	v_lshrrev_b32_e32 v34, 5, v32
	v_and_b32_e32 v39, 7, v32
	v_lshrrev_b32_e32 v50, 3, v32
	v_lshrrev_b32_e32 v51, 6, v152
	s_nop 0
	v_readfirstlane_b32 s6, v51
	v_mul_u32_u24_e32 v36, 33, v34
	v_add_lshl_u32 v36, v36, v33, 2
	v_mul_u32_u24_e32 v37, 0x108, v39
	v_add_lshl_u32 v37, v37, v50, 2
	s_lshl_b32 s7, s6, 14
	v_add_u32_e32 v36, s7, v36
	v_add_u32_e32 v37, s7, v37
	s_sub_i32 s7, s2, 48
	s_lshl_b32 s7, s7, 3
	s_add_i32 s7, s7, s6
	s_waitcnt vmcnt(0)
	v_readfirstlane_b32 s24, v40
	v_readfirstlane_b32 s25, v41
	v_readfirstlane_b32 s26, v42
	v_readfirstlane_b32 s27, v43
	v_readfirstlane_b32 s28, v44
	v_readfirstlane_b32 s29, v45
	v_readfirstlane_b32 s30, v46
	v_readfirstlane_b32 s31, v47
	v_readfirstlane_b32 s34, v48
	v_readfirstlane_b32 s35, v49
.Ldw_item:
	s_mov_b32 s40, 0
	s_movk_i32 s37, 0x400
	s_movk_i32 s38, 0x400
	s_cmpk_ge_u32 s7, 0x200
	s_cbranch_scc1 .Ldw_m1
	s_mov_b64 s[8:9], s[24:25]
	s_mov_b32 s36, 0x800000
	s_mov_b32 s39, s7
	s_branch .Ldw_dec
.Ldw_m1:
	s_cmpk_ge_u32 s7, 0x500
	s_cbranch_scc1 .Ldw_m2
	s_mov_b64 s[8:9], s[26:27]
	s_mov_b32 s36, 0xa00000
	s_movk_i32 s38, 0x600
	s_mov_b32 s40, 1
	s_sub_i32 s39, s7, 0x200
	s_branch .Ldw_dec
.Ldw_m2:
	s_cmpk_ge_u32 s7, 0x700
	s_cbranch_scc1 .Ldw_m3
	s_mov_b64 s[8:9], s[28:29]
	s_mov_b32 s36, 0xd00000
	s_sub_i32 s39, s7, 0x500
	s_branch .Ldw_dec
.Ldw_m3:
	s_cmpk_ge_u32 s7, 0x1700
	s_cbranch_scc1 .Ldw_m5
	s_movk_i32 s38, 0x1000
	s_sub_i32 s39, s7, 0x700
	s_lshr_b32 s41, s39, 11
	s_and_b32 s39, s39, 0x7ff
	s_lshl_b32 s42, s41, 24
	s_add_u32 s8, s30, s42
	s_addc_u32 s9, s31, 0
	s_lshl_b32 s42, s41, 23
	s_add_i32 s36, s42, 0x1000000
	s_branch .Ldw_dec
.Ldw_m5:
	s_movk_i32 s37, 0x1000
	s_sub_i32 s39, s7, 0x1700
	s_lshr_b32 s41, s39, 11
	s_and_b32 s39, s39, 0x7ff
	s_lshl_b32 s42, s41, 24
	s_add_u32 s8, s34, s42
	s_addc_u32 s9, s35, 0
	s_lshl_b32 s42, s41, 23
	s_add_i32 s36, s42, 0x2000000
.Ldw_dec:
	s_cmpk_eq_u32 s38, 0x600
	s_cbranch_scc1 .Ldw_d48
	s_lshr_b32 s41, s38, 5
	s_ff1_i32_b32 s42, s41
	s_lshr_b32 s43, s39, s42
	s_add_i32 s41, s41, -1
	s_and_b32 s44, s39, s41
	s_branch .Ldw_d
.Ldw_d48:
	s_mul_i32 s43, s39, 0xaaab
	s_lshr_b32 s43, s43, 21
	s_mul_i32 s44, s43, 48
	s_sub_i32 s44, s39, s44
.Ldw_d:
	s_lshl_b32 s43, s43, 6
	s_lshl_b32 s44, s44, 5
	s_andn2_b32 s45, s44, 0xff
	s_bfe_u32 s46, s44, 0x10005
	s_lshl_b32 s46, s46, 7
	s_add_i32 s45, s45, s46
	s_bfe_u32 s46, s44, 0x20006
	s_lshl_b32 s46, s46, 5
	s_add_i32 s45, s45, s46
	s_cmp_lg_u32 s40, 0
	s_cselect_b32 s45, s45, s44
	s_mul_i32 s46, s43, s38
	s_add_i32 s46, s46, s44
	s_lshl_b32 s46, s46, 2
	s_add_u32 s8, s8, s46
	s_addc_u32 s9, s9, 0
	s_mul_i32 s46, s45, s37
	s_add_i32 s46, s46, s43
	s_lshl_b32 s46, s46, 1
	s_add_u32 s10, s78, s36
	s_addc_u32 s11, s79, 0
	s_add_u32 s10, s10, s46
	s_addc_u32 s11, s11, 0
	s_lshl_b32 s12, s38, 3
	s_lshl_b32 s13, s37, 4
	v_mul_lo_u32 v35, v34, s38
	v_add_lshl_u32 v35, v35, v33, 2
	v_mul_lo_u32 v38, v50, s37
	v_lshl_add_u32 v38, v39, 3, v38
	v_lshlrev_b32_e32 v38, 1, v38
	global_load_dword v62, v35, s[8:9]
	s_add_u32 s8, s8, s12
	s_addc_u32 s9, s9, 0
	global_load_dword v63, v35, s[8:9]
	s_add_u32 s8, s8, s12
	s_addc_u32 s9, s9, 0
	global_load_dword v64, v35, s[8:9]
	s_add_u32 s8, s8, s12
	s_addc_u32 s9, s9, 0
	global_load_dword v65, v35, s[8:9]
	s_add_u32 s8, s8, s12
	s_addc_u32 s9, s9, 0
	global_load_dword v66, v35, s[8:9]
	s_add_u32 s8, s8, s12
	s_addc_u32 s9, s9, 0
	global_load_dword v67, v35, s[8:9]
	s_add_u32 s8, s8, s12
	s_addc_u32 s9, s9, 0
	global_load_dword v68, v35, s[8:9]
	s_add_u32 s8, s8, s12
	s_addc_u32 s9, s9, 0
	global_load_dword v69, v35, s[8:9]
	s_add_u32 s8, s8, s12
	s_addc_u32 s9, s9, 0
	global_load_dword v70, v35, s[8:9]
	s_add_u32 s8, s8, s12
	s_addc_u32 s9, s9, 0
	global_load_dword v71, v35, s[8:9]
	s_add_u32 s8, s8, s12
	s_addc_u32 s9, s9, 0
	global_load_dword v72, v35, s[8:9]
	s_add_u32 s8, s8, s12
	s_addc_u32 s9, s9, 0
	global_load_dword v73, v35, s[8:9]
	s_add_u32 s8, s8, s12
	s_addc_u32 s9, s9, 0
	global_load_dword v74, v35, s[8:9]
	s_add_u32 s8, s8, s12
	s_addc_u32 s9, s9, 0
	global_load_dword v75, v35, s[8:9]
	s_add_u32 s8, s8, s12
	s_addc_u32 s9, s9, 0
	global_load_dword v76, v35, s[8:9]
	s_add_u32 s8, s8, s12
	s_addc_u32 s9, s9, 0
	global_load_dword v77, v35, s[8:9]
	s_add_u32 s8, s8, s12
	s_addc_u32 s9, s9, 0
	global_load_dword v78, v35, s[8:9]
	s_add_u32 s8, s8, s12
	s_addc_u32 s9, s9, 0
	global_load_dword v79, v35, s[8:9]
	s_add_u32 s8, s8, s12
	s_addc_u32 s9, s9, 0
	global_load_dword v80, v35, s[8:9]
	s_add_u32 s8, s8, s12
	s_addc_u32 s9, s9, 0
	global_load_dword v81, v35, s[8:9]
	s_add_u32 s8, s8, s12
	s_addc_u32 s9, s9, 0
	global_load_dword v82, v35, s[8:9]
	s_add_u32 s8, s8, s12
	s_addc_u32 s9, s9, 0
	global_load_dword v83, v35, s[8:9]
	s_add_u32 s8, s8, s12
	s_addc_u32 s9, s9, 0
	global_load_dword v84, v35, s[8:9]
	s_add_u32 s8, s8, s12
	s_addc_u32 s9, s9, 0
	global_load_dword v85, v35, s[8:9]
	s_add_u32 s8, s8, s12
	s_addc_u32 s9, s9, 0
	global_load_dword v86, v35, s[8:9]
	s_add_u32 s8, s8, s12
	s_addc_u32 s9, s9, 0
	global_load_dword v87, v35, s[8:9]
	s_add_u32 s8, s8, s12
	s_addc_u32 s9, s9, 0
	global_load_dword v88, v35, s[8:9]
	s_add_u32 s8, s8, s12
	s_addc_u32 s9, s9, 0
	global_load_dword v89, v35, s[8:9]
	s_add_u32 s8, s8, s12
	s_addc_u32 s9, s9, 0
	global_load_dword v90, v35, s[8:9]
	s_add_u32 s8, s8, s12
	s_addc_u32 s9, s9, 0
	global_load_dword v91, v35, s[8:9]
	s_add_u32 s8, s8, s12
	s_addc_u32 s9, s9, 0
	global_load_dword v92, v35, s[8:9]
	s_add_u32 s8, s8, s12
	s_addc_u32 s9, s9, 0
	global_load_dword v93, v35, s[8:9]
	s_waitcnt vmcnt(31)
; #define LAS __attribute__((address_space(3)))
; __device__ __forceinline__ unsigned pkbf(float lo, float hi) { f32x2_t v = {lo, hi}; bf16x2_t b = __builtin_convertvector(v, bf16x2_t); return __builtin_bit_cast(unsigned, b); }
; __device__ __forceinline__ void transpose_item(const float* W, int K, int N, bf16_t* WT, bool perm, LAS float* scr, int item, int lane) {
;     ...
;     for (int i = 0; i < 32; ++i) { const int kk = 2 * i + (lane >> 5); scr[kk * 33 + (lane & 31)] = W[(size_t)(k0 + kk) * N + n0 + (lane & 31)]; }
;     asm volatile("s_waitcnt lgkmcnt(0)" ::: "memory");
;     const int c = lane & 7;
; #pragma unroll
;     for (int j = 0; j < 4; ++j) { const int n = (lane >> 3) + 8 * j; const LAS float* s = scr + (8 * c) * 33 + n;
;         u32x4 o; o.x = pkbf(s[0 * 33], s[1 * 33]); o.y = pkbf(s[2 * 33], s[3 * 33]); o.z = pkbf(s[4 * 33], s[5 * 33]); o.w = pkbf(s[6 * 33], s[7 * 33]);
;         *(u32x4*)(WT + (size_t)(r0 + n) * K + k0 + 8 * c) = o; }
;     asm volatile("s_waitcnt lgkmcnt(0)" ::: "memory");
; __device__ __forceinline__ void xcd_barrier(const XcdBarrier& b) {
;     asm volatile("s_waitcnt vmcnt(0)" ::: "memory");
;     __syncthreads();
;     if (threadIdx.x == 0) {
;         unsigned* bar = b.bar;
;         __builtin_amdgcn_s_waitcnt(0);
;         unsigned nloc = b.st[0], nx = b.st[1];
;         if (nloc == 0u) { xcd_barrier_complete(bar, b.x, nloc, nx); b.st[0] = nloc; b.st[1] = nx; }
	ds_write_b32 v36, v62
	s_waitcnt vmcnt(30)
	ds_write_b32 v36, v63 offset:264
	s_waitcnt vmcnt(29)
	ds_write_b32 v36, v64 offset:528
	s_waitcnt vmcnt(28)
	ds_write_b32 v36, v65 offset:792
	s_waitcnt vmcnt(27)
	ds_write_b32 v36, v66 offset:1056
	s_waitcnt vmcnt(26)
	ds_write_b32 v36, v67 offset:1320
	s_waitcnt vmcnt(25)
	ds_write_b32 v36, v68 offset:1584
	s_waitcnt vmcnt(24)
	ds_write_b32 v36, v69 offset:1848
	s_waitcnt vmcnt(23)
	ds_write_b32 v36, v70 offset:2112
	s_waitcnt vmcnt(22)
	ds_write_b32 v36, v71 offset:2376
	s_waitcnt vmcnt(21)
	ds_write_b32 v36, v72 offset:2640
	s_waitcnt vmcnt(20)
	ds_write_b32 v36, v73 offset:2904
	s_waitcnt vmcnt(19)
	ds_write_b32 v36, v74 offset:3168
	s_waitcnt vmcnt(18)
	ds_write_b32 v36, v75 offset:3432
	s_waitcnt vmcnt(17)
	ds_write_b32 v36, v76 offset:3696
	s_waitcnt vmcnt(16)
	ds_write_b32 v36, v77 offset:3960
	s_waitcnt vmcnt(15)
	ds_write_b32 v36, v78 offset:4224
	s_waitcnt vmcnt(14)
	ds_write_b32 v36, v79 offset:4488
	s_waitcnt vmcnt(13)
	ds_write_b32 v36, v80 offset:4752
	s_waitcnt vmcnt(12)
	ds_write_b32 v36, v81 offset:5016
	s_waitcnt vmcnt(11)
	ds_write_b32 v36, v82 offset:5280
	s_waitcnt vmcnt(10)
	ds_write_b32 v36, v83 offset:5544
	s_waitcnt vmcnt(9)
	ds_write_b32 v36, v84 offset:5808
	s_waitcnt vmcnt(8)
	ds_write_b32 v36, v85 offset:6072
	s_waitcnt vmcnt(7)
	ds_write_b32 v36, v86 offset:6336
	s_waitcnt vmcnt(6)
	ds_write_b32 v36, v87 offset:6600
	s_waitcnt vmcnt(5)
	ds_write_b32 v36, v88 offset:6864
	s_waitcnt vmcnt(4)
	ds_write_b32 v36, v89 offset:7128
	s_waitcnt vmcnt(3)
	ds_write_b32 v36, v90 offset:7392
	s_waitcnt vmcnt(2)
	ds_write_b32 v36, v91 offset:7656
	s_waitcnt vmcnt(1)
	ds_write_b32 v36, v92 offset:7920
	s_waitcnt vmcnt(0)
	ds_write_b32 v36, v93 offset:8184
	s_waitcnt lgkmcnt(0)
	ds_read2_b32 v[104:105], v37 offset0:0 offset1:33
	ds_read2_b32 v[106:107], v37 offset0:66 offset1:99
	ds_read2_b32 v[108:109], v37 offset0:132 offset1:165
	ds_read2_b32 v[110:111], v37 offset0:198 offset1:231
	ds_read2_b32 v[112:113], v37 offset0:8 offset1:41
	ds_read2_b32 v[114:115], v37 offset0:74 offset1:107
	ds_read2_b32 v[116:117], v37 offset0:140 offset1:173
	ds_read2_b32 v[118:119], v37 offset0:206 offset1:239
	ds_read2_b32 v[120:121], v37 offset0:16 offset1:49
	ds_read2_b32 v[122:123], v37 offset0:82 offset1:115
	ds_read2_b32 v[124:125], v37 offset0:148 offset1:181
	ds_read2_b32 v[126:127], v37 offset0:214 offset1:247
	ds_read2_b32 v[128:129], v37 offset0:24 offset1:57
	ds_read2_b32 v[130:131], v37 offset0:90 offset1:123
	ds_read2_b32 v[132:133], v37 offset0:156 offset1:189
	ds_read2_b32 v[134:135], v37 offset0:222 offset1:255
	s_waitcnt lgkmcnt(12)
	v_cvt_pk_bf16_f32 v200, v104, v105
	v_cvt_pk_bf16_f32 v201, v106, v107
	v_cvt_pk_bf16_f32 v202, v108, v109
	v_cvt_pk_bf16_f32 v203, v110, v111
	s_waitcnt lgkmcnt(8)
	v_cvt_pk_bf16_f32 v204, v112, v113
	v_cvt_pk_bf16_f32 v205, v114, v115
	v_cvt_pk_bf16_f32 v206, v116, v117
	v_cvt_pk_bf16_f32 v207, v118, v119
	s_waitcnt lgkmcnt(4)
	v_cvt_pk_bf16_f32 v208, v120, v121
	v_cvt_pk_bf16_f32 v209, v122, v123
	v_cvt_pk_bf16_f32 v210, v124, v125
	v_cvt_pk_bf16_f32 v211, v126, v127
	s_waitcnt lgkmcnt(0)
	v_cvt_pk_bf16_f32 v212, v128, v129
	v_cvt_pk_bf16_f32 v213, v130, v131
	v_cvt_pk_bf16_f32 v214, v132, v133
	v_cvt_pk_bf16_f32 v215, v134, v135
	global_store_dwordx4 v38, v[200:203], s[10:11]
	s_add_u32 s10, s10, s13
	s_addc_u32 s11, s11, 0
	global_store_dwordx4 v38, v[204:207], s[10:11]
	s_add_u32 s10, s10, s13
	s_addc_u32 s11, s11, 0
	global_store_dwordx4 v38, v[208:211], s[10:11]
	s_add_u32 s10, s10, s13
	s_addc_u32 s11, s11, 0
	global_store_dwordx4 v38, v[212:215], s[10:11]
	s_addk_i32 s7, 0x680
	s_cmpk_lt_u32 s7, 0x2700
	s_cbranch_scc1 .Ldw_item
.Ldw_done:
.LBB0_288:
	s_getreg_b32 s6, hwreg(HW_REG_XCC_ID, 0, 4)
	s_waitcnt vmcnt(0)
	s_waitcnt vmcnt(0)
	s_barrier
	s_and_saveexec_b64 s[0:1], s[54:55]
	s_cbranch_execz .LBB0_340
	v_readlane_b32 s7, v240, 14
	s_waitcnt vmcnt(0) expcnt(0) lgkmcnt(0)
	s_and_b32 s12, s6, 15
	v_mov_b32_e32 v0, s7
	ds_read_b32 v2, v0
	v_readlane_b32 s7, v240, 15
	s_waitcnt lgkmcnt(0)
	v_cmp_ne_u32_e32 vcc, 0, v2
	v_mov_b32_e32 v0, s7
	ds_read_b32 v0, v0
	s_cbranch_vccnz .LBB0_304
	v_readlane_b32 s8, v241, 2
	v_readlane_b32 s9, v241, 3
	s_load_dwordx2 s[6:7], s[8:9], 0x4
	s_mov_b32 s14, 1
	s_waitcnt lgkmcnt(0)
	s_mul_i32 s13, s6, s3
	s_mul_i32 s13, s13, s7
	s_branch .LBB0_292
